# dil and SWA band items: redundant end-of-item s_barrier removed (next item's prologue touches no LDS; its chunk loop opens with its own barrier before the first LDS write)
# baseline (speedup 1.0000x reference)
; __device__ __forceinline__ unsigned pk_bf16(float lo, float hi) { const f32x2 v = {lo, hi}; const bf16v2 b = __builtin_convertvector(v, bf16v2); return __builtin_bit_cast(unsigned, b); }
; __device__ __forceinline__ float bf_lo(unsigned u) { return __uint_as_float(u << 16); }
; __device__ __forceinline__ float bf_hi(unsigned u) { return __uint_as_float(u & 0xffff0000u); }
; __device__ __forceinline__ float silu_f(float v) { return v * __builtin_amdgcn_rcpf(1.0f + __builtin_amdgcn_exp2f(-LOG2E * v)); }
; __device__ __forceinline__ float xsum32(float v) { const auto r = __builtin_amdgcn_permlane32_swap(__float_as_uint(v), __float_as_uint(v), false, false); return __uint_as_float(r[0]) + __uint_as_float(r[1]); }
; template <int HD, int DV, int HW, int MODE> ...
;     ...
;     const float lt = xsum32(l), inv = 1.0f / lt;
;     const size_t tok = tok0 + (size_t)r * (iw + ql);
;     if (MODE == 0) {
;         if (hh == 0) lsep[tok * 8] = m + __builtin_amdgcn_logf(lt);
; #pragma unroll
;         for (int t = 0; t < NTV; ++t)
; #pragma unroll
;             for (int i4 = 0; i4 < 4; ++i4) { u32x2 wv; wv.x = pk_bf16(O[t][4 * i4] * inv, O[t][4 * i4 + 1] * inv); wv.y = pk_bf16(O[t][4 * i4 + 2] * inv, O[t][4 * i4 + 3] * inv);
;                 *(u32x2*)(op + tok * old + 32 * t + 8 * i4 + 4 * hh) = wv; }
;     } else {
; #pragma unroll
;         for (int t = 0; t < NTV; ++t)
; #pragma unroll
;             for (int i4 = 0; i4 < 4; ++i4) { const int dv = 32 * t + 8 * i4 + 4 * hh; const u32x2 z = *(const u32x2*)(zp + tok * ld + dv);
;                 u32x2 wv; wv.x = pk_bf16(O[t][4 * i4] * inv * silu_f(bf_lo(z.x)), O[t][4 * i4 + 1] * inv * silu_f(bf_hi(z.x))); wv.y = pk_bf16(O[t][4 * i4 + 2] * inv * silu_f(bf_lo(z.y)), O[t][4 * i4 + 3] * inv * silu_f(bf_hi(z.y)));
;                 *(u32x2*)(op + tok * old + dv) = wv; }
;     }
;     __syncthreads();
.LBB0_83:
	s_or_b64 exec, exec, s[40:41]
	v_div_scale_f32 v2, s[4:5], v1, v1, 1.0
	v_rcp_f32_e32 v3, v2
	v_div_scale_f32 v4, vcc, 1.0, v1, 1.0
	s_lshl_b64 s[4:5], s[26:27], 25
	v_fma_f32 v5, -v2, v3, 1.0
	v_fmac_f32_e32 v3, v5, v3
	v_mul_f32_e32 v5, v4, v3
	v_fma_f32 v6, -v2, v5, v4
	v_fmac_f32_e32 v5, v6, v3
	s_add_u32 s2, s90, s4
	v_fma_f32 v2, -v2, v5, v4
	s_addc_u32 s5, s91, s5
	v_div_fmas_f32 v2, v2, v3, v5
	s_add_u32 s4, s2, s22
	v_div_fixup_f32 v2, v2, v1, 1.0
	s_addc_u32 s5, s5, 0
	v_lshlrev_b64 v[4:5], 11, v[160:161]
	v_lshl_add_u64 v[4:5], s[4:5], 0, v[4:5]
	v_mov_b32_e32 v163, v0
	v_lshl_add_u64 v[4:5], v[4:5], 0, v[162:163]
	v_bfe_u32 v136, v207, 5, 1
	v_lshlrev_b32_e32 v136, 3, v136
	v_mov_b32_e32 v137, v0
	v_lshl_add_u64 v[4:5], v[4:5], 0, v[136:137]
	v_pk_mul_f32 v[6:7], v[64:65], v[2:3] op_sel_hi:[1,0]
	v_pk_mul_f32 v[8:9], v[66:67], v[2:3] op_sel_hi:[1,0]
	v_cvt_pk_bf16_f32 v128, v6, v7
	v_cvt_pk_bf16_f32 v129, v8, v9
	v_pk_mul_f32 v[6:7], v[68:69], v[2:3] op_sel_hi:[1,0]
	v_pk_mul_f32 v[8:9], v[70:71], v[2:3] op_sel_hi:[1,0]
	v_cvt_pk_bf16_f32 v130, v6, v7
	v_cvt_pk_bf16_f32 v131, v8, v9
	s_nop 1
	v_permlane32_swap_b32_e32 v128, v130
	v_permlane32_swap_b32_e32 v129, v131
	global_store_dwordx4 v[4:5], v[128:131], off
	v_pk_mul_f32 v[6:7], v[72:73], v[2:3] op_sel_hi:[1,0]
	v_pk_mul_f32 v[8:9], v[74:75], v[2:3] op_sel_hi:[1,0]
	v_cvt_pk_bf16_f32 v132, v6, v7
	v_cvt_pk_bf16_f32 v133, v8, v9
	v_pk_mul_f32 v[6:7], v[76:77], v[2:3] op_sel_hi:[1,0]
	v_pk_mul_f32 v[8:9], v[78:79], v[2:3] op_sel_hi:[1,0]
	v_cvt_pk_bf16_f32 v134, v6, v7
	v_cvt_pk_bf16_f32 v135, v8, v9
	s_nop 1
	v_permlane32_swap_b32_e32 v132, v134
	v_permlane32_swap_b32_e32 v133, v135
	global_store_dwordx4 v[4:5], v[132:135], off offset:32
	v_pk_mul_f32 v[6:7], v[48:49], v[2:3] op_sel_hi:[1,0]
	v_pk_mul_f32 v[8:9], v[50:51], v[2:3] op_sel_hi:[1,0]
	v_cvt_pk_bf16_f32 v128, v6, v7
	v_cvt_pk_bf16_f32 v129, v8, v9
	v_pk_mul_f32 v[6:7], v[52:53], v[2:3] op_sel_hi:[1,0]
	v_pk_mul_f32 v[8:9], v[54:55], v[2:3] op_sel_hi:[1,0]
	v_cvt_pk_bf16_f32 v130, v6, v7
	v_cvt_pk_bf16_f32 v131, v8, v9
	s_nop 1
	v_permlane32_swap_b32_e32 v128, v130
	v_permlane32_swap_b32_e32 v129, v131
	global_store_dwordx4 v[4:5], v[128:131], off offset:64
	v_pk_mul_f32 v[6:7], v[56:57], v[2:3] op_sel_hi:[1,0]
	v_pk_mul_f32 v[8:9], v[58:59], v[2:3] op_sel_hi:[1,0]
	v_cvt_pk_bf16_f32 v132, v6, v7
	v_cvt_pk_bf16_f32 v133, v8, v9
	v_pk_mul_f32 v[6:7], v[60:61], v[2:3] op_sel_hi:[1,0]
	v_pk_mul_f32 v[8:9], v[62:63], v[2:3] op_sel_hi:[1,0]
	v_cvt_pk_bf16_f32 v134, v6, v7
	v_cvt_pk_bf16_f32 v135, v8, v9
	s_nop 1
	v_permlane32_swap_b32_e32 v132, v134
	v_permlane32_swap_b32_e32 v133, v135
	global_store_dwordx4 v[4:5], v[132:135], off offset:96
	v_pk_mul_f32 v[6:7], v[32:33], v[2:3] op_sel_hi:[1,0]
	v_pk_mul_f32 v[8:9], v[34:35], v[2:3] op_sel_hi:[1,0]
	v_cvt_pk_bf16_f32 v128, v6, v7
	v_cvt_pk_bf16_f32 v129, v8, v9
	v_pk_mul_f32 v[6:7], v[36:37], v[2:3] op_sel_hi:[1,0]
	v_pk_mul_f32 v[8:9], v[38:39], v[2:3] op_sel_hi:[1,0]
	v_cvt_pk_bf16_f32 v130, v6, v7
	v_cvt_pk_bf16_f32 v131, v8, v9
	s_nop 1
	v_permlane32_swap_b32_e32 v128, v130
	v_permlane32_swap_b32_e32 v129, v131
	global_store_dwordx4 v[4:5], v[128:131], off offset:128
	v_pk_mul_f32 v[6:7], v[40:41], v[2:3] op_sel_hi:[1,0]
	v_pk_mul_f32 v[8:9], v[42:43], v[2:3] op_sel_hi:[1,0]
	v_cvt_pk_bf16_f32 v132, v6, v7
	v_cvt_pk_bf16_f32 v133, v8, v9
	v_pk_mul_f32 v[6:7], v[44:45], v[2:3] op_sel_hi:[1,0]
	v_pk_mul_f32 v[8:9], v[46:47], v[2:3] op_sel_hi:[1,0]
	v_cvt_pk_bf16_f32 v134, v6, v7
	v_cvt_pk_bf16_f32 v135, v8, v9
	s_nop 1
	v_permlane32_swap_b32_e32 v132, v134
	v_permlane32_swap_b32_e32 v133, v135
	global_store_dwordx4 v[4:5], v[132:135], off offset:160
	v_pk_mul_f32 v[6:7], v[16:17], v[2:3] op_sel_hi:[1,0]
	v_pk_mul_f32 v[8:9], v[18:19], v[2:3] op_sel_hi:[1,0]
	v_cvt_pk_bf16_f32 v128, v6, v7
	v_cvt_pk_bf16_f32 v129, v8, v9
	v_pk_mul_f32 v[6:7], v[20:21], v[2:3] op_sel_hi:[1,0]
	v_pk_mul_f32 v[8:9], v[22:23], v[2:3] op_sel_hi:[1,0]
	v_cvt_pk_bf16_f32 v130, v6, v7
	v_cvt_pk_bf16_f32 v131, v8, v9
	s_nop 1
	v_permlane32_swap_b32_e32 v128, v130
	v_permlane32_swap_b32_e32 v129, v131
	global_store_dwordx4 v[4:5], v[128:131], off offset:192
	v_pk_mul_f32 v[6:7], v[24:25], v[2:3] op_sel_hi:[1,0]
	v_pk_mul_f32 v[8:9], v[26:27], v[2:3] op_sel_hi:[1,0]
	v_cvt_pk_bf16_f32 v132, v6, v7
	v_cvt_pk_bf16_f32 v133, v8, v9
	v_pk_mul_f32 v[6:7], v[28:29], v[2:3] op_sel_hi:[1,0]
	v_pk_mul_f32 v[8:9], v[30:31], v[2:3] op_sel_hi:[1,0]
	v_cvt_pk_bf16_f32 v134, v6, v7
	v_cvt_pk_bf16_f32 v135, v8, v9
	s_nop 1
	v_permlane32_swap_b32_e32 v132, v134
	v_permlane32_swap_b32_e32 v133, v135
	global_store_dwordx4 v[4:5], v[132:135], off offset:224
	s_add_i32 s15, s15, s50
	s_cmpk_gt_i32 s15, 0x5ff
	s_cbranch_scc1 .LBB0_73

; __device__ __forceinline__ unsigned pk_bf16(float lo, float hi) { const f32x2 v = {lo, hi}; const bf16v2 b = __builtin_convertvector(v, bf16v2); return __builtin_bit_cast(unsigned, b); }
; __device__ __forceinline__ float bf_lo(unsigned u) { return __uint_as_float(u << 16); }
; __device__ __forceinline__ float bf_hi(unsigned u) { return __uint_as_float(u & 0xffff0000u); }
; __device__ __forceinline__ float silu_f(float v) { return v * __builtin_amdgcn_rcpf(1.0f + __builtin_amdgcn_exp2f(-LOG2E * v)); }
; __device__ __forceinline__ float xsum32(float v) { const auto r = __builtin_amdgcn_permlane32_swap(__float_as_uint(v), __float_as_uint(v), false, false); return __uint_as_float(r[0]) + __uint_as_float(r[1]); }
; template <int HD, int DV, int HW, int MODE> ...
;     ...
;     const float lt = xsum32(l), inv = 1.0f / lt;
;     const size_t tok = tok0 + (size_t)r * (iw + ql);
;     if (MODE == 0) {
;         if (hh == 0) lsep[tok * 8] = m + __builtin_amdgcn_logf(lt);
; #pragma unroll
;         for (int t = 0; t < NTV; ++t)
; #pragma unroll
;             for (int i4 = 0; i4 < 4; ++i4) { u32x2 wv; wv.x = pk_bf16(O[t][4 * i4] * inv, O[t][4 * i4 + 1] * inv); wv.y = pk_bf16(O[t][4 * i4 + 2] * inv, O[t][4 * i4 + 3] * inv);
;                 *(u32x2*)(op + tok * old + 32 * t + 8 * i4 + 4 * hh) = wv; }
;     } else {
; #pragma unroll
;         for (int t = 0; t < NTV; ++t)
; #pragma unroll
;             for (int i4 = 0; i4 < 4; ++i4) { const int dv = 32 * t + 8 * i4 + 4 * hh; const u32x2 z = *(const u32x2*)(zp + tok * ld + dv);
;                 u32x2 wv; wv.x = pk_bf16(O[t][4 * i4] * inv * silu_f(bf_lo(z.x)), O[t][4 * i4 + 1] * inv * silu_f(bf_hi(z.x))); wv.y = pk_bf16(O[t][4 * i4 + 2] * inv * silu_f(bf_lo(z.y)), O[t][4 * i4 + 3] * inv * silu_f(bf_hi(z.y)));
;                 *(u32x2*)(op + tok * old + dv) = wv; }
.LBB0_157:
	v_mov_b32_e32 v1, v101
	s_nop 1
	v_permlane32_swap_b32_e32 v101, v1
	v_add_f32_e32 v1, v101, v1
	v_div_scale_f32 v2, s[22:23], v1, v1, 1.0
	v_rcp_f32_e32 v3, v2
	s_lshl_b32 s2, s46, 1
	s_add_u32 s4, s80, s2
	s_addc_u32 s5, s81, 0
	v_fma_f32 v4, -v2, v3, 1.0
	v_fmac_f32_e32 v3, v4, v3
	v_div_scale_f32 v4, vcc, 1.0, v1, 1.0
	v_mul_f32_e32 v5, v4, v3
	v_readlane_b32 s10, v253, 10
	v_fma_f32 v6, -v2, v5, v4
	s_add_u32 s10, s10, s2
	v_readlane_b32 s2, v253, 11
	v_fmac_f32_e32 v5, v6, v3
	s_addc_u32 s11, s2, 0
	v_fma_f32 v2, -v2, v5, v4
	v_div_fmas_f32 v2, v2, v3, v5
	v_lshl_add_u64 v[4:5], v[98:99], 1, s[10:11]
	v_lshlrev_b64 v[6:7], 11, v[96:97]
	v_mov_b32_e32 v101, v0
	v_lshl_add_u64 v[8:9], s[4:5], 0, v[6:7]
	v_lshl_add_u64 v[6:7], v[4:5], 0, v[100:101]
	global_load_dwordx2 v[4:5], v[6:7], off
	global_load_dwordx2 v[182:183], v[6:7], off offset:16
	global_load_dwordx2 v[184:185], v[6:7], off offset:32
	global_load_dwordx2 v[186:187], v[6:7], off offset:48
	global_load_dwordx2 v[188:189], v[6:7], off offset:64
	global_load_dwordx2 v[190:191], v[6:7], off offset:80
	global_load_dwordx2 v[192:193], v[6:7], off offset:96
	global_load_dwordx2 v[194:195], v[6:7], off offset:112
	v_div_fixup_f32 v2, v2, v1, 1.0
	v_pk_mul_f32 v[14:15], v[32:33], v[2:3] op_sel_hi:[1,0]
	v_readlane_b32 s2, v254, 49
	s_add_i32 s21, s21, s50
	s_add_i32 s15, s15, s2
	s_cmpk_gt_i32 s21, 0x7ff
	s_waitcnt vmcnt(7)
	v_lshlrev_b32_e32 v10, 16, v4
	v_mul_f32_e32 v1, 0xbfb8aa3b, v10
	v_exp_f32_e32 v1, v1
	v_and_b32_e32 v11, 0xffff0000, v4
	v_lshlrev_b32_e32 v4, 16, v5
	v_and_b32_e32 v5, 0xffff0000, v5
	v_add_f32_e32 v1, 1.0, v1
	v_rcp_f32_e32 v12, v1
	v_mul_f32_e32 v1, 0xbfb8aa3b, v11
	v_exp_f32_e32 v1, v1
	s_nop 0
	v_add_f32_e32 v1, 1.0, v1
	v_rcp_f32_e32 v13, v1
	v_mul_f32_e32 v1, 0xbfb8aa3b, v4
	v_exp_f32_e32 v1, v1
	v_pk_mul_f32 v[10:11], v[12:13], v[10:11]
	s_nop 0
	v_pk_mul_f32 v[10:11], v[14:15], v[10:11]
	v_add_f32_e32 v1, 1.0, v1
	v_rcp_f32_e32 v12, v1
	v_mul_f32_e32 v1, 0xbfb8aa3b, v5
	v_exp_f32_e32 v1, v1
	v_pk_mul_f32 v[14:15], v[34:35], v[2:3] op_sel_hi:[1,0]
	v_cvt_pk_bf16_f32 v10, v10, v11
	v_add_f32_e32 v1, 1.0, v1
	v_rcp_f32_e32 v13, v1
	s_nop 0
	v_pk_mul_f32 v[4:5], v[12:13], v[4:5]
	s_nop 0
	v_pk_mul_f32 v[4:5], v[14:15], v[4:5]
	v_pk_mul_f32 v[14:15], v[36:37], v[2:3] op_sel_hi:[1,0]
	v_cvt_pk_bf16_f32 v11, v4, v5
	v_lshl_add_u64 v[4:5], v[8:9], 0, v[100:101]
	s_nop 0
	global_store_dwordx2 v[4:5], v[10:11], off
	s_waitcnt vmcnt(7)
	v_lshlrev_b32_e32 v10, 16, v182
	v_mul_f32_e32 v1, 0xbfb8aa3b, v10
	v_exp_f32_e32 v1, v1
	v_and_b32_e32 v11, 0xffff0000, v182
	v_add_f32_e32 v1, 1.0, v1
	v_rcp_f32_e32 v12, v1
	v_mul_f32_e32 v1, 0xbfb8aa3b, v11
	v_exp_f32_e32 v1, v1
	s_nop 0
	v_add_f32_e32 v1, 1.0, v1
	v_rcp_f32_e32 v13, v1
	s_nop 0
	v_pk_mul_f32 v[10:11], v[12:13], v[10:11]
	s_nop 0
	v_pk_mul_f32 v[10:11], v[14:15], v[10:11]
	v_pk_mul_f32 v[14:15], v[38:39], v[2:3] op_sel_hi:[1,0]
	v_cvt_pk_bf16_f32 v8, v10, v11
	v_lshlrev_b32_e32 v10, 16, v183
	v_mul_f32_e32 v1, 0xbfb8aa3b, v10
	v_exp_f32_e32 v1, v1
	v_and_b32_e32 v11, 0xffff0000, v183
	v_add_f32_e32 v1, 1.0, v1
	v_rcp_f32_e32 v12, v1
	v_mul_f32_e32 v1, 0xbfb8aa3b, v11
	v_exp_f32_e32 v1, v1
	s_nop 0
	v_add_f32_e32 v1, 1.0, v1
	v_rcp_f32_e32 v13, v1
	s_nop 0
	v_pk_mul_f32 v[10:11], v[12:13], v[10:11]
	s_nop 0
	v_pk_mul_f32 v[10:11], v[14:15], v[10:11]
	v_pk_mul_f32 v[14:15], v[40:41], v[2:3] op_sel_hi:[1,0]
	v_cvt_pk_bf16_f32 v9, v10, v11
	global_store_dwordx2 v[4:5], v[8:9], off offset:16
	s_waitcnt vmcnt(7)
	v_lshlrev_b32_e32 v10, 16, v184
	v_mul_f32_e32 v1, 0xbfb8aa3b, v10
	v_exp_f32_e32 v1, v1
	v_and_b32_e32 v11, 0xffff0000, v184
	v_add_f32_e32 v1, 1.0, v1
	v_rcp_f32_e32 v12, v1
	v_mul_f32_e32 v1, 0xbfb8aa3b, v11
	v_exp_f32_e32 v1, v1
	s_nop 0
	v_add_f32_e32 v1, 1.0, v1
	v_rcp_f32_e32 v13, v1
	s_nop 0
	v_pk_mul_f32 v[10:11], v[12:13], v[10:11]
	s_nop 0
	v_pk_mul_f32 v[10:11], v[14:15], v[10:11]
	v_pk_mul_f32 v[14:15], v[42:43], v[2:3] op_sel_hi:[1,0]
	v_cvt_pk_bf16_f32 v8, v10, v11
	v_lshlrev_b32_e32 v10, 16, v185
	v_mul_f32_e32 v1, 0xbfb8aa3b, v10
	v_exp_f32_e32 v1, v1
	v_and_b32_e32 v11, 0xffff0000, v185
	v_add_f32_e32 v1, 1.0, v1
	v_rcp_f32_e32 v12, v1
	v_mul_f32_e32 v1, 0xbfb8aa3b, v11
	v_exp_f32_e32 v1, v1
	s_nop 0
	v_add_f32_e32 v1, 1.0, v1
	v_rcp_f32_e32 v13, v1
	s_nop 0
	v_pk_mul_f32 v[10:11], v[12:13], v[10:11]
	s_nop 0
	v_pk_mul_f32 v[10:11], v[14:15], v[10:11]
	v_pk_mul_f32 v[14:15], v[44:45], v[2:3] op_sel_hi:[1,0]
	v_cvt_pk_bf16_f32 v9, v10, v11
	global_store_dwordx2 v[4:5], v[8:9], off offset:32
	s_waitcnt vmcnt(7)
; __device__ __forceinline__ unsigned pk_bf16(float lo, float hi) { const f32x2 v = {lo, hi}; const bf16v2 b = __builtin_convertvector(v, bf16v2); return __builtin_bit_cast(unsigned, b); }
; __device__ __forceinline__ float bf_lo(unsigned u) { return __uint_as_float(u << 16); }
; __device__ __forceinline__ float bf_hi(unsigned u) { return __uint_as_float(u & 0xffff0000u); }
; __device__ __forceinline__ float silu_f(float v) { return v * __builtin_amdgcn_rcpf(1.0f + __builtin_amdgcn_exp2f(-LOG2E * v)); }
; template <int HD, int DV, int HW, int MODE> ...
;     ...
;             for (int i4 = 0; i4 < 4; ++i4) { const int dv = 32 * t + 8 * i4 + 4 * hh; const u32x2 z = *(const u32x2*)(zp + tok * ld + dv);
;                 u32x2 wv; wv.x = pk_bf16(O[t][4 * i4] * inv * silu_f(bf_lo(z.x)), O[t][4 * i4 + 1] * inv * silu_f(bf_hi(z.x))); wv.y = pk_bf16(O[t][4 * i4 + 2] * inv * silu_f(bf_lo(z.y)), O[t][4 * i4 + 3] * inv * silu_f(bf_hi(z.y)));
;                 *(u32x2*)(op + tok * old + dv) = wv; }
;     }
;     __syncthreads();
	v_lshlrev_b32_e32 v10, 16, v186
	v_mul_f32_e32 v1, 0xbfb8aa3b, v10
	v_exp_f32_e32 v1, v1
	v_and_b32_e32 v11, 0xffff0000, v186
	v_add_f32_e32 v1, 1.0, v1
	v_rcp_f32_e32 v12, v1
	v_mul_f32_e32 v1, 0xbfb8aa3b, v11
	v_exp_f32_e32 v1, v1
	s_nop 0
	v_add_f32_e32 v1, 1.0, v1
	v_rcp_f32_e32 v13, v1
	s_nop 0
	v_pk_mul_f32 v[10:11], v[12:13], v[10:11]
	s_nop 0
	v_pk_mul_f32 v[10:11], v[14:15], v[10:11]
	v_pk_mul_f32 v[14:15], v[46:47], v[2:3] op_sel_hi:[1,0]
	v_cvt_pk_bf16_f32 v8, v10, v11
	v_lshlrev_b32_e32 v10, 16, v187
	v_mul_f32_e32 v1, 0xbfb8aa3b, v10
	v_exp_f32_e32 v1, v1
	v_and_b32_e32 v11, 0xffff0000, v187
	v_add_f32_e32 v1, 1.0, v1
	v_rcp_f32_e32 v12, v1
	v_mul_f32_e32 v1, 0xbfb8aa3b, v11
	v_exp_f32_e32 v1, v1
	s_nop 0
	v_add_f32_e32 v1, 1.0, v1
	v_rcp_f32_e32 v13, v1
	s_nop 0
	v_pk_mul_f32 v[10:11], v[12:13], v[10:11]
	s_nop 0
	v_pk_mul_f32 v[10:11], v[14:15], v[10:11]
	v_pk_mul_f32 v[14:15], v[16:17], v[2:3] op_sel_hi:[1,0]
	v_cvt_pk_bf16_f32 v9, v10, v11
	global_store_dwordx2 v[4:5], v[8:9], off offset:48
	s_waitcnt vmcnt(7)
	v_lshlrev_b32_e32 v10, 16, v188
	v_mul_f32_e32 v1, 0xbfb8aa3b, v10
	v_exp_f32_e32 v1, v1
	v_and_b32_e32 v11, 0xffff0000, v188
	v_add_f32_e32 v1, 1.0, v1
	v_rcp_f32_e32 v12, v1
	v_mul_f32_e32 v1, 0xbfb8aa3b, v11
	v_exp_f32_e32 v1, v1
	s_nop 0
	v_add_f32_e32 v1, 1.0, v1
	v_rcp_f32_e32 v13, v1
	s_nop 0
	v_pk_mul_f32 v[10:11], v[12:13], v[10:11]
	s_nop 0
	v_pk_mul_f32 v[10:11], v[14:15], v[10:11]
	v_pk_mul_f32 v[14:15], v[18:19], v[2:3] op_sel_hi:[1,0]
	v_cvt_pk_bf16_f32 v8, v10, v11
	v_lshlrev_b32_e32 v10, 16, v189
	v_mul_f32_e32 v1, 0xbfb8aa3b, v10
	v_exp_f32_e32 v1, v1
	v_and_b32_e32 v11, 0xffff0000, v189
	v_add_f32_e32 v1, 1.0, v1
	v_rcp_f32_e32 v12, v1
	v_mul_f32_e32 v1, 0xbfb8aa3b, v11
	v_exp_f32_e32 v1, v1
	s_nop 0
	v_add_f32_e32 v1, 1.0, v1
	v_rcp_f32_e32 v13, v1
	s_nop 0
	v_pk_mul_f32 v[10:11], v[12:13], v[10:11]
	s_nop 0
	v_pk_mul_f32 v[10:11], v[14:15], v[10:11]
	v_pk_mul_f32 v[14:15], v[20:21], v[2:3] op_sel_hi:[1,0]
	v_cvt_pk_bf16_f32 v9, v10, v11
	global_store_dwordx2 v[4:5], v[8:9], off offset:64
	s_waitcnt vmcnt(7)
	v_lshlrev_b32_e32 v10, 16, v190
	v_mul_f32_e32 v1, 0xbfb8aa3b, v10
	v_exp_f32_e32 v1, v1
	v_and_b32_e32 v11, 0xffff0000, v190
	v_add_f32_e32 v1, 1.0, v1
	v_rcp_f32_e32 v12, v1
	v_mul_f32_e32 v1, 0xbfb8aa3b, v11
	v_exp_f32_e32 v1, v1
	s_nop 0
	v_add_f32_e32 v1, 1.0, v1
	v_rcp_f32_e32 v13, v1
	s_nop 0
	v_pk_mul_f32 v[10:11], v[12:13], v[10:11]
	s_nop 0
	v_pk_mul_f32 v[10:11], v[14:15], v[10:11]
	v_pk_mul_f32 v[14:15], v[22:23], v[2:3] op_sel_hi:[1,0]
	v_cvt_pk_bf16_f32 v8, v10, v11
	v_lshlrev_b32_e32 v10, 16, v191
	v_mul_f32_e32 v1, 0xbfb8aa3b, v10
	v_exp_f32_e32 v1, v1
	v_and_b32_e32 v11, 0xffff0000, v191
	v_add_f32_e32 v1, 1.0, v1
	v_rcp_f32_e32 v12, v1
	v_mul_f32_e32 v1, 0xbfb8aa3b, v11
	v_exp_f32_e32 v1, v1
	s_nop 0
	v_add_f32_e32 v1, 1.0, v1
	v_rcp_f32_e32 v13, v1
	s_nop 0
	v_pk_mul_f32 v[10:11], v[12:13], v[10:11]
	s_nop 0
	v_pk_mul_f32 v[10:11], v[14:15], v[10:11]
	v_pk_mul_f32 v[14:15], v[24:25], v[2:3] op_sel_hi:[1,0]
	v_cvt_pk_bf16_f32 v9, v10, v11
	global_store_dwordx2 v[4:5], v[8:9], off offset:80
	s_waitcnt vmcnt(7)
	v_lshlrev_b32_e32 v10, 16, v192
	v_mul_f32_e32 v1, 0xbfb8aa3b, v10
	v_exp_f32_e32 v1, v1
	v_and_b32_e32 v11, 0xffff0000, v192
	v_add_f32_e32 v1, 1.0, v1
	v_rcp_f32_e32 v12, v1
	v_mul_f32_e32 v1, 0xbfb8aa3b, v11
	v_exp_f32_e32 v1, v1
	s_nop 0
	v_add_f32_e32 v1, 1.0, v1
	v_rcp_f32_e32 v13, v1
	s_nop 0
	v_pk_mul_f32 v[10:11], v[12:13], v[10:11]
	s_nop 0
	v_pk_mul_f32 v[10:11], v[14:15], v[10:11]
	v_pk_mul_f32 v[14:15], v[26:27], v[2:3] op_sel_hi:[1,0]
	v_cvt_pk_bf16_f32 v8, v10, v11
	v_lshlrev_b32_e32 v10, 16, v193
	v_mul_f32_e32 v1, 0xbfb8aa3b, v10
	v_exp_f32_e32 v1, v1
	v_and_b32_e32 v11, 0xffff0000, v193
	v_add_f32_e32 v1, 1.0, v1
	v_rcp_f32_e32 v12, v1
	v_mul_f32_e32 v1, 0xbfb8aa3b, v11
	v_exp_f32_e32 v1, v1
	s_nop 0
	v_add_f32_e32 v1, 1.0, v1
	v_rcp_f32_e32 v13, v1
	s_nop 0
	v_pk_mul_f32 v[10:11], v[12:13], v[10:11]
	s_nop 0
	v_pk_mul_f32 v[10:11], v[14:15], v[10:11]
	v_pk_mul_f32 v[12:13], v[28:29], v[2:3] op_sel_hi:[1,0]
	v_cvt_pk_bf16_f32 v9, v10, v11
	global_store_dwordx2 v[4:5], v[8:9], off offset:96
	v_pk_mul_f32 v[2:3], v[30:31], v[2:3] op_sel_hi:[1,0]
	s_waitcnt vmcnt(7)
	v_lshlrev_b32_e32 v8, 16, v194
	v_mul_f32_e32 v1, 0xbfb8aa3b, v8
	v_exp_f32_e32 v1, v1
	v_and_b32_e32 v9, 0xffff0000, v194
	v_add_f32_e32 v1, 1.0, v1
	v_rcp_f32_e32 v10, v1
	v_mul_f32_e32 v1, 0xbfb8aa3b, v9
	v_exp_f32_e32 v1, v1
	s_nop 0
	v_add_f32_e32 v1, 1.0, v1
	v_rcp_f32_e32 v11, v1
	s_nop 0
	v_pk_mul_f32 v[8:9], v[10:11], v[8:9]
	s_nop 0
	v_pk_mul_f32 v[8:9], v[12:13], v[8:9]
	s_nop 0
	v_cvt_pk_bf16_f32 v6, v8, v9
	v_lshlrev_b32_e32 v8, 16, v195
	v_mul_f32_e32 v1, 0xbfb8aa3b, v8
	v_exp_f32_e32 v1, v1
	v_and_b32_e32 v9, 0xffff0000, v195
	v_add_f32_e32 v1, 1.0, v1
	v_rcp_f32_e32 v10, v1
	v_mul_f32_e32 v1, 0xbfb8aa3b, v9
	v_exp_f32_e32 v1, v1
	s_nop 0
	v_add_f32_e32 v1, 1.0, v1
	v_rcp_f32_e32 v11, v1
	s_nop 0
	v_pk_mul_f32 v[8:9], v[10:11], v[8:9]
	s_nop 0
	v_pk_mul_f32 v[2:3], v[2:3], v[8:9]
	s_nop 0
	v_cvt_pk_bf16_f32 v7, v2, v3
	global_store_dwordx2 v[4:5], v[6:7], off offset:112
	s_cbranch_scc1 .LBB0_64
